# every per-segment s_setprio deleted, one static s_setprio 1 for waves 0-3 (the other half) at kernel entry
# speedup vs baseline: 1.0116x; 1.0052x over previous
; DI int half_() { return __builtin_amdgcn_readfirstlane((int)(threadIdx.x >> 8)); }
; DI void grid_barrier(unsigned* bar, unsigned gen) {
;     ...
;   if (threadIdx.x == 0) {
;     __builtin_amdgcn_fence(__ATOMIC_RELEASE, "agent");
;     const unsigned grp = blockIdx.x & 15u;
;     const unsigned nblk = (gridDim.x + 15u - grp) >> 4;
; __global__ void __launch_bounds__(512, 2) mega(Params p_unused, int ph0, int ph1) {
;   __shared__ __attribute__((aligned(16))) unsigned char lds_all[LDS_BYTES];
;   unsigned char* ldsb = lds_all + half_() * LDS_HALF;
;   cg::grid_group grid = cg::this_grid();
;   for (int ph = ph0; ph < ph1; ++ph) {
;     const __attribute__((address_space(4))) Params* pp = (const __attribute__((address_space(4))) Params*)__builtin_amdgcn_kernarg_segment_ptr();
;     asm volatile("" : "+s"(pp));
;     PREF p = *pp;
;     if (ph1 < 0) grid.sync();
;     if (ph > ph0) grid_barrier(p.bar, (unsigned)(ph - ph0));
;     if (ph == 0) { run_phase<9>(p, 0, ldsb, lds_all); continue; }
;     int l = (ph - 1) / NPH_LAYER; const int j = (ph - 1) % NPH_LAYER;
;     asm volatile("" : "+s"(l));
.LBB0_1:
	s_lshr_b32 s33, s0, 8
	v_readlane_b32 s0, v254, 1
	v_readlane_b32 s1, v254, 2
	s_add_u32 s2, s0, 0x1a8
	s_addc_u32 s3, s1, 0
	v_writelane_b32 v254, s2, 5
	v_lshrrev_b32_e32 v1, 20, v0
	v_lshrrev_b32_e32 v0, 10, v0
	v_writelane_b32 v254, s3, 6
	v_or_b32_e32 v0, v0, v1
	s_movk_i32 s2, 0x3ff
	v_and_or_b32 v0, v0, s2, v168
	v_readlane_b32 s8, v254, 3
	v_cmp_eq_u32_e64 s[2:3], 0, v0
	v_readlane_b32 s9, v254, 4
	s_load_dword s5, s[0:1], 0x1a8
	v_writelane_b32 v254, s2, 7
	s_cmp_lt_i32 s9, 0
	s_cselect_b64 s[0:1], -1, 0
	v_writelane_b32 v254, s3, 8
	v_cmp_eq_u32_e64 s[2:3], 0, v168
	s_waitcnt lgkmcnt(0)
	s_lshr_b32 s45, s5, 3
	s_mul_i32 s33, s33, 0x12400
	v_writelane_b32 v254, s2, 9
	v_cndmask_b32_e64 v0, 0, 1, s[0:1]
	v_cmp_ne_u32_e64 s[0:1], 1, v0
	v_writelane_b32 v254, s3, 10
	v_mbcnt_lo_u32_b32 v0, -1, 0
	v_readlane_b32 s4, v254, 0
	s_and_b32 s2, s4, 15
	s_xor_b32 s3, s2, 15
	s_add_i32 s3, s5, s3
	s_lshr_b32 s3, s3, 4
	s_lshl_b32 s2, s2, 6
	s_lshr_b32 s46, s4, 3
	s_cmpk_lt_u32 s4, 0x200
	v_writelane_b32 v254, s3, 11
	s_cselect_b64 s[6:7], -1, 0
	s_lshl_b32 s3, s4, 4
	s_and_b32 s47, s3, 0x70
	s_lshl_b32 s3, s4, 3
	s_lshl_b32 s48, s5, 3
	v_writelane_b32 v254, s6, 12
	s_cmpk_lt_i32 s4, 0x100
	s_mov_b32 s53, 0
	v_writelane_b32 v254, s7, 13
	s_cselect_b64 s[6:7], -1, 0
	v_writelane_b32 v254, s6, 14
	s_ashr_i32 s49, s48, 31
	s_lshl_b32 s64, s5, 9
	v_writelane_b32 v254, s7, 15
	s_add_i32 s6, s33, 0x12000
	v_writelane_b32 v254, s6, 16
	s_lshl_b32 s6, s4, 9
	v_writelane_b32 v254, s6, 17
	s_lshl_b64 s[6:7], s[48:49], 11
	v_writelane_b32 v254, s6, 18
	s_ashr_i32 s65, s64, 31
	s_lshl_b32 s70, s4, 1
	v_writelane_b32 v254, s7, 19
	v_writelane_b32 v254, s3, 20
	s_addk_i32 s3, 0x4000
	v_writelane_b32 v254, s3, 21
	s_lshl_b32 s3, s4, 8
	v_writelane_b32 v254, s3, 22
	s_lshl_b32 s3, s5, 8
	v_writelane_b32 v254, s3, 23
	s_add_i32 s3, s33, 0x4000
	v_writelane_b32 v254, s3, 24
	s_lshl_b32 s3, s4, 6
	v_writelane_b32 v254, s3, 25
	s_lshl_b64 s[6:7], s[64:65], 4
	v_writelane_b32 v254, s6, 26
	s_lshl_b32 s3, s5, 10
	s_lshl_b32 s71, s5, 1
	v_writelane_b32 v254, s7, 27
	s_lshl_b64 s[6:7], s[64:65], 5
	v_writelane_b32 v254, s6, 28
	s_lshl_b32 s81, s4, 7
	s_lshl_b32 s84, s5, 7
	v_writelane_b32 v254, s7, 29
	s_lshl_b64 s[6:7], s[48:49], 12
	v_writelane_b32 v254, s6, 30
	s_lshl_b32 s85, s5, 6
	s_movk_i32 s66, 0x200
	v_writelane_b32 v254, s7, 31
	v_writelane_b32 v254, s5, 32
	v_writelane_b32 v254, s3, 33
	s_lshl_b64 s[4:5], s[64:65], 2
	v_writelane_b32 v254, s4, 34
	v_and_b32_e32 v169, 0xff, v168
	s_movk_i32 s67, 0x100
	v_writelane_b32 v254, s5, 35
	v_writelane_b32 v254, s0, 36
	s_lshl_b64 s[72:73], s[64:65], 6
	v_mov_b32_e32 v1, 0
	v_writelane_b32 v254, s1, 37
	s_lshl_b32 s0, s2, 2
	v_writelane_b32 v254, s0, 38
	v_writelane_b32 v254, s45, 39
	v_writelane_b32 v254, s46, 40
	v_writelane_b32 v254, s47, 41
	s_mov_b32 s0, s48
	v_writelane_b32 v254, s0, 42
	s_mov_b32 s88, 0x10000
	v_mov_b32_e32 v170, 0x1000
	v_writelane_b32 v254, s1, 43
	s_mov_b32 s0, s64
	s_mov_b64 s[76:77], 0x80
	s_mov_b64 s[78:79], 0x40080
	s_mov_b64 s[42:43], 0x12b0100
	s_mov_b64 s[82:83], 0x100
	s_mov_b64 s[86:87], 0x40100
	s_mov_b64 s[90:91], 0x180
	s_movk_i32 s89, 0x180
	s_movk_i32 s92, 0x210
	s_movk_i32 s93, 0x80
	v_mov_b32_e32 v171, 0x3727c5ac
	s_mov_b32 s61, 0x800000
	s_movk_i32 s80, 0x1000
	s_mov_b64 s[50:51], 0x580100
	s_mov_b64 s[38:39], 0x980100
	s_mov_b64 s[4:5], 0x580180
	s_mov_b64 s[74:75], 0x980180
	s_movk_i32 s60, 0x1540
	s_movk_i32 s96, 0x300
	s_movk_i32 s97, 0x90
	s_mov_b32 s94, 0xff800000
	v_mbcnt_hi_u32_b32 v172, -1, v0
	v_mov_b32_e32 v163, 1.0
	s_mov_b64 s[2:3], 0xaa000
	v_mov_b32_e32 v173, 0x358637bd
	s_movk_i32 s95, 0x400
	s_mov_b64 s[6:7], 0x40180
	s_movk_i32 s58, 0xaa0
	s_movk_i32 s59, 0x600
	s_movk_i32 s54, 0x2a80
	v_mov_b32_e32 v174, 0x3c0881c4
	v_mov_b32_e32 v175, 0xbab64f3b
	v_mov_b32_e32 v176, 0xff800000
	v_mov_b32_e32 v177, 0x7f800000
	v_not_b32_e32 v178, 63
	v_not_b32_e32 v179, 31
	v_mov_b32_e32 v180, 0x7fc00000
	v_mov_b32_e32 v181, 0x37000000
	s_mov_b32 s34, s8
	v_writelane_b32 v254, s0, 44
	s_nop 1
	v_writelane_b32 v254, s1, 45
	v_readfirstlane_b32 s0, v168
	s_lshr_b32 s0, s0, 8
	s_cmp_eq_u32 s0, 0
	s_cbranch_scc0 .Lmy_prio_done
	s_setprio 1
